# c24: c23 + last in-proj tile round split in halves across all workgroups
# speedup vs baseline: 1.0204x; 1.0050x over previous
; #define LDSAS __attribute__((address_space(3)))
; #define G_ISSUE(kt, st) do { G_ISSUE1(kt, st, 0); G_ISSUE1(kt, st, 1); G_ISSUE1(kt, st, 2); G_ISSUE1(kt, st, 3); } while (0)
; template <bool LOWREG = false>
; __device__ __forceinline__ void gemm_core(const bf16_t* __restrict__ A, int lda, const bf16_t* __restrict__ Bt, int ldb, int K, f32x4 (&acc)[8][4], unsigned char* smem, int tid) {
;     asm volatile("" : "+v"(tid));
;     const int lane = tid & 63, w = __builtin_amdgcn_readfirstlane(tid >> 6), wm = w >> 2, wn = w & 3, idx = lane & 15, kq = lane >> 4;
;     unsigned offA[4], offB[4];
; #pragma unroll
;     for (int j = 0; j < 4; ++j) { const int row = (j * 8 + w) * 8 + (lane >> 3), c = (lane & 7) ^ ((row >> 1) & 7);
;         offA[j] = (unsigned)(row * lda + c * 8) * 2u; offB[j] = (unsigned)(row * ldb + c * 8) * 2u; }
; #pragma unroll
;     for (int mi = 0; mi < 8; ++mi)
; #pragma unroll
;         for (int ni = 0; ni < 4; ++ni) acc[mi][ni] = (f32x4){0.f, 0.f, 0.f, 0.f};
;     LDSAS unsigned char* lds = (LDSAS unsigned char*)smem;
;     ...
;     const int nk = K >> 6;
;     G_ISSUE(0, 0);
;     asm volatile("s_waitcnt vmcnt(0)" ::: "memory");
;     __syncthreads();
;     const int swz = (idx >> 1) & 7;
;     const int aoff = (wm * 128 + idx) * 128, boff = G_AB + (wn * 64 + idx) * 128;
; __device__ void gemm1_phase(const Params& p, int l, int hb, unsigned char* smem) {
;     ...
;     for (int t = blockIdx.x; t < NTILES; t += gridDim.x) {
;         const int grp = t / GRP, r = t % GRP, jx = NT * (r & 7) + (r >> 3), mt = grp * 8 + (jx & 7), nt = jx >> 3;
;         const int m0 = mt * 256, n0 = nt * 256;
;         f32x4 acc[8][4];
;         int tid = threadIdx.x;
;         gemm_core(H + (size_t)m0 * 1024, 1024, Wt + (size_t)n0 * 1024, 1024, 1024, acc, smem, tid);
.Lg1_nosplit:
	s_mul_hi_i32 s9, s99, 0x78787879
	s_lshr_b32 s11, s9, 31
	s_ashr_i32 s9, s9, 7
	s_add_i32 s9, s9, s11
	s_mul_i32 s11, s9, 0x110
	s_sub_i32 s11, s99, s11
	s_and_b32 s12, s11, 7
	s_mul_i32 s12, s12, 34
	s_ashr_i32 s11, s11, 3
	s_add_i32 s12, s12, s11
	s_lshl_b32 s11, s12, 8
	s_lshl_b32 s9, s9, 11
	s_and_b32 s11, s11, 0x700
	s_or_b32 s56, s11, s9
	s_lshl_b32 s11, s12, 5
	s_ashr_i32 s57, s56, 31
	s_and_b32 s36, s11, 0xffffff00
	s_lshl_b64 s[16:17], s[56:57], 11
	s_add_u32 s18, s92, s16
	s_addc_u32 s19, s93, s17
	s_ashr_i32 s37, s36, 31
	s_lshl_b64 s[20:21], s[36:37], 11
	v_mov_b32_e32 v0, v210
	s_add_u32 s22, s94, s20
	s_addc_u32 s23, s95, s21
	v_readfirstlane_b32 s12, v0
	s_ashr_i32 s24, s12, 6
	s_and_b32 s101, s24, 3
	s_cmp_lg_u32 s101, 0
	s_cselect_b32 s101, 1, 2
	s_cmp_eq_u32 s36, 0x2100
	s_cselect_b32 s101, s101, 0
	s_lshr_b32 s98, s24, 2
	s_cmp_lg_u32 s98, s100
	s_cselect_b32 s98, 1, 0
	s_cmp_lt_i32 s100, 0
	s_cselect_b32 s98, 0, s98
	s_or_b32 s101, s101, s98
	v_bfe_u32 v2, v0, 3, 3
	v_lshl_or_b32 v3, s24, 3, v2
	v_lshrrev_b32_e32 v4, 1, v3
	v_xor_b32_e32 v4, v4, v0
	v_lshlrev_b32_e32 v4, 4, v4
	s_lshl_b32 s9, s24, 10
	v_and_b32_e32 v4, 0x70, v4
	s_add_i32 s9, s9, 0
	v_lshl_or_b32 v3, v3, 11, v4
	s_mov_b32 m0, s9
	v_add_u32_e32 v5, 0x20000, v3
	global_load_lds_dwordx4 v3, s[18:19]
	s_add_i32 m0, s9, 0x8000
	v_add_u32_e32 v6, 0x40000, v3
	global_load_lds_dwordx4 v3, s[22:23]
	s_add_i32 m0, s9, 0x2000
	v_add_u32_e32 v7, 0x60000, v3
	global_load_lds_dwordx4 v5, s[18:19]
	s_add_i32 m0, s9, 0xa000
	v_and_b32_e32 v1, 15, v0
	global_load_lds_dwordx4 v5, s[22:23]
	s_add_i32 m0, s9, 0x4000
	v_bfe_u32 v8, v0, 4, 2
	global_load_lds_dwordx4 v6, s[18:19]
	s_add_i32 m0, s9, 0xc000
	v_lshrrev_b32_e32 v3, 1, v0
	global_load_lds_dwordx4 v6, s[22:23]
	s_add_i32 m0, s9, 0x6000
	v_bfe_u32 v0, v0, 1, 3
	global_load_lds_dwordx4 v7, s[18:19]
	s_add_i32 m0, s9, 0xe000
	s_lshr_b32 s18, s12, 1
	global_load_lds_dwordx4 v7, s[22:23]
	s_and_b32 s18, s18, 0x1ffff80
	s_and_b32 s12, s12, 0xc0
	v_or_b32_e32 v5, s18, v1
	v_or_b32_e32 v1, s12, v1
	s_lshl_b32 s12, s24, 14
	s_add_u32 s16, s96, s16
	v_lshlrev_b32_e32 v149, 7, v5
	v_bitop3_b32 v0, v8, v0, 4 bitop3:0x36
	v_lshlrev_b32_e32 v5, 11, v2
	s_addc_u32 s17, s97, s17
	s_add_i32 s18, s12, 0x20000
	v_lshlrev_b32_e32 v147, 7, v1
	v_bitop3_b32 v1, v8, v3, 7 bitop3:0x78
	v_lshlrev_b32_e32 v146, 4, v0
	v_or3_b32 v80, s12, v5, v4
	v_or3_b32 v0, s18, v5, v4
	s_add_i32 s18, s12, 0x40000
	s_add_i32 s12, s12, 0x60000
	v_lshlrev_b32_e32 v148, 4, v1
	v_mov_b32_e32 v1, v81
	v_or3_b32 v2, s18, v5, v4
	v_mov_b32_e32 v3, v81
	v_or3_b32 v4, s12, v5, v4
	v_mov_b32_e32 v5, v81
	v_lshl_add_u64 v[130:131], s[16:17], 0, v[80:81]
	v_lshl_add_u64 v[132:133], s[16:17], 0, v[0:1]
	v_lshl_add_u64 v[134:135], s[16:17], 0, v[2:3]
	v_lshl_add_u64 v[136:137], s[16:17], 0, v[4:5]
	s_add_u32 s16, s64, s20
	s_waitcnt vmcnt(0)
	s_addc_u32 s17, s65, s21
	v_lshl_add_u64 v[140:141], s[16:17], 0, v[0:1]
	v_mov_b32_e32 v0, 0
	v_lshl_add_u64 v[138:139], s[16:17], 0, v[80:81]
	v_lshl_add_u64 v[142:143], s[16:17], 0, v[2:3]
	v_lshl_add_u64 v[144:145], s[16:17], 0, v[4:5]
	s_mov_b32 s12, 0
	s_mov_b64 s[38:39], 0
	v_mov_b32_e32 v1, v0
	v_mov_b32_e32 v2, v0
	v_mov_b32_e32 v3, v0
	v_mov_b32_e32 v4, v0
	v_mov_b32_e32 v5, v0
	v_mov_b32_e32 v6, v0
	v_mov_b32_e32 v7, v0
	v_mov_b32_e32 v8, v0
	v_mov_b32_e32 v9, v0
	s_waitcnt vmcnt(0)
	v_mov_b32_e32 v10, v0
	v_mov_b32_e32 v11, v0
	v_mov_b32_e32 v12, v0
	v_mov_b32_e32 v13, v0
	v_mov_b32_e32 v14, v0
	v_mov_b32_e32 v15, v0
	v_mov_b32_e32 v16, v0
	v_mov_b32_e32 v17, v0
	v_mov_b32_e32 v18, v0
	v_mov_b32_e32 v19, v0
	v_mov_b32_e32 v20, v0
	v_mov_b32_e32 v21, v0
	v_mov_b32_e32 v22, v0
	v_mov_b32_e32 v23, v0
	v_mov_b32_e32 v24, v0
	v_mov_b32_e32 v25, v0
	v_mov_b32_e32 v26, v0
	v_mov_b32_e32 v27, v0
	v_mov_b32_e32 v28, v0
	v_mov_b32_e32 v29, v0
	v_mov_b32_e32 v30, v0
	v_mov_b32_e32 v31, v0
	v_mov_b32_e32 v32, v0
	v_mov_b32_e32 v33, v0
	v_mov_b32_e32 v34, v0
	v_mov_b32_e32 v35, v0
	v_mov_b32_e32 v36, v0
	v_mov_b32_e32 v37, v0
	v_mov_b32_e32 v38, v0
	v_mov_b32_e32 v39, v0
	v_mov_b32_e32 v40, v0
	v_mov_b32_e32 v41, v0
	v_mov_b32_e32 v42, v0
	v_mov_b32_e32 v43, v0
	v_mov_b32_e32 v44, v0
	v_mov_b32_e32 v45, v0
	v_mov_b32_e32 v46, v0
	v_mov_b32_e32 v47, v0
	v_mov_b32_e32 v48, v0
	v_mov_b32_e32 v49, v0
	v_mov_b32_e32 v50, v0
	v_mov_b32_e32 v51, v0
	v_mov_b32_e32 v52, v0
	v_mov_b32_e32 v53, v0
	v_mov_b32_e32 v54, v0
	v_mov_b32_e32 v55, v0
	v_mov_b32_e32 v56, v0
	v_mov_b32_e32 v57, v0
	v_mov_b32_e32 v58, v0
	v_mov_b32_e32 v59, v0
	v_mov_b32_e32 v60, v0
	v_mov_b32_e32 v61, v0
	v_mov_b32_e32 v62, v0
	v_mov_b32_e32 v63, v0
	v_mov_b32_e32 v64, v0
	v_mov_b32_e32 v65, v0
	v_mov_b32_e32 v66, v0
	v_mov_b32_e32 v67, v0
	v_mov_b32_e32 v68, v0
	v_mov_b32_e32 v69, v0
	v_mov_b32_e32 v70, v0
	v_mov_b32_e32 v71, v0
	v_mov_b32_e32 v72, v0
	v_mov_b32_e32 v73, v0
	v_mov_b32_e32 v74, v0
	v_mov_b32_e32 v75, v0
	v_mov_b32_e32 v76, v0
	v_mov_b32_e32 v77, v0
	v_mov_b32_e32 v78, v0
	v_mov_b32_e32 v79, v0
	v_mov_b32_e32 v82, v0
	v_mov_b32_e32 v83, v0
	v_mov_b32_e32 v84, v0
	v_mov_b32_e32 v85, v0
	v_mov_b32_e32 v86, v0
	v_mov_b32_e32 v87, v0
	v_mov_b32_e32 v88, v0
	v_mov_b32_e32 v89, v0
	v_mov_b32_e32 v90, v0
	v_mov_b32_e32 v91, v0
	v_mov_b32_e32 v92, v0
	v_mov_b32_e32 v93, v0
	v_mov_b32_e32 v94, v0
	v_mov_b32_e32 v95, v0
	v_mov_b32_e32 v96, v0
	v_mov_b32_e32 v97, v0
	v_mov_b32_e32 v98, v0
	v_mov_b32_e32 v99, v0
	v_mov_b32_e32 v100, v0
	v_mov_b32_e32 v101, v0
	v_mov_b32_e32 v102, v0
	v_mov_b32_e32 v103, v0
	v_mov_b32_e32 v104, v0
	v_mov_b32_e32 v105, v0
	v_mov_b32_e32 v106, v0
	v_mov_b32_e32 v107, v0
	v_mov_b32_e32 v108, v0
	v_mov_b32_e32 v109, v0
	v_mov_b32_e32 v110, v0
	v_mov_b32_e32 v111, v0
	v_mov_b32_e32 v112, v0
	v_mov_b32_e32 v113, v0
	v_mov_b32_e32 v114, v0
	v_mov_b32_e32 v115, v0
	v_mov_b32_e32 v116, v0
	v_mov_b32_e32 v117, v0
	v_mov_b32_e32 v118, v0
	v_mov_b32_e32 v119, v0
	v_mov_b32_e32 v120, v0
	v_mov_b32_e32 v121, v0
	v_mov_b32_e32 v122, v0
	v_mov_b32_e32 v123, v0
	v_mov_b32_e32 v124, v0
	v_mov_b32_e32 v125, v0
	v_mov_b32_e32 v126, v0
	v_mov_b32_e32 v127, v0
	v_mov_b32_e32 v128, v0
	v_mov_b32_e32 v129, v0
	s_waitcnt lgkmcnt(0)
	s_barrier
